# lru_tile local scan: LDS reads prefetched 32 steps at a time instead of 32 serialized read/drain round trips
# speedup vs baseline: 1.0278x; 1.0022x over previous
.LBB0_650:
	s_or_b64 exec, exec, s[10:11]
	s_lshl_b32 s4, s4, 16
	v_readlane_b32 s10, v249, 32
	s_add_u32 s10, s10, s4
	v_readlane_b32 s4, v249, 33
	s_addc_u32 s11, s4, 0
	s_ashr_i32 s4, s5, 2
	s_and_b32 s5, s4, -16
	v_and_b32_e32 v18, 15, v39
	v_bfi_b32 v36, -16, s4, v39
	s_addk_i32 s5, 0x80
	s_waitcnt vmcnt(2)
	v_cvt_pk_bf16_f32 v6, v6, v7
	v_cvt_pk_bf16_f32 v7, v8, v9
	v_cvt_pk_bf16_f32 v9, v4, v5
	v_ashrrev_i32_e32 v37, 31, v36
	v_or_b32_e32 v4, s5, v18
	v_cvt_pk_bf16_f32 v8, v2, v3
	s_movk_i32 s18, 0x110
	v_bfe_u32 v44, v39, 4, 2
	v_lshlrev_b64 v[2:3], 8, v[36:37]
	v_ashrrev_i32_e32 v5, 31, v4
	v_mul_lo_u32 v41, v22, s18
	v_lshl_add_u64 v[2:3], s[10:11], 0, v[2:3]
	v_lshlrev_b32_e32 v0, 4, v44
	v_lshlrev_b64 v[4:5], 8, v[4:5]
	s_waitcnt vmcnt(0)
	v_cvt_pk_bf16_f32 v14, v14, v15
	v_cvt_pk_bf16_f32 v15, v16, v17
	v_cvt_pk_bf16_f32 v16, v10, v11
	v_cvt_pk_bf16_f32 v17, v12, v13
	v_add3_u32 v35, 0, v41, v34
	v_lshl_add_u64 v[2:3], v[2:3], 0, v[0:1]
	v_lshl_add_u64 v[4:5], s[10:11], 0, v[4:5]
	ds_write_b128 v35, v[14:17]
	ds_write_b128 v35, v[6:9] offset:16
	s_waitcnt lgkmcnt(0)
	s_barrier
	v_lshl_add_u64 v[4:5], v[4:5], 0, v[0:1]
	global_load_dwordx4 v[6:9], v[2:3], off
	global_load_dwordx4 v[10:13], v[4:5], off
	v_mul_u32_u24_e32 v14, 0x110, v18
	v_add3_u32 v0, 0, v0, v14
	ds_read_b128 v[14:17], v0
	ds_read_b128 v[22:25], v0 offset:4352
	ds_read_b128 v[30:33], v0 offset:8704
	ds_read_b128 v[50:53], v0 offset:13056
	s_movk_i32 s4, 0x50
	v_readlane_b32 s12, v250, 57
	v_readlane_b32 s13, v250, 58
	s_add_i32 s10, s68, s16
	v_add_u32_e32 v42, s10, v36
	v_ashrrev_i32_e32 v43, 31, v42
	s_waitcnt vmcnt(1) lgkmcnt(3)
	v_mfma_f32_16x16x32_bf16 v[18:21], v[14:17], v[6:9], 0
	s_waitcnt vmcnt(0)
	v_mfma_f32_16x16x32_bf16 v[14:17], v[14:17], v[10:13], 0
	s_waitcnt lgkmcnt(2)
	v_mfma_f32_16x16x32_bf16 v[26:29], v[22:25], v[6:9], 0
	v_mfma_f32_16x16x32_bf16 v[22:25], v[22:25], v[10:13], 0
	s_waitcnt lgkmcnt(1)
	v_mfma_f32_16x16x32_bf16 v[46:49], v[30:33], v[6:9], 0
	v_mfma_f32_16x16x32_bf16 v[30:33], v[30:33], v[10:13], 0
	s_waitcnt lgkmcnt(0)
	v_mfma_f32_16x16x32_bf16 v[6:9], v[50:53], v[6:9], 0
	v_mfma_f32_16x16x32_bf16 v[10:13], v[50:53], v[10:13], 0
	global_load_dwordx4 v[50:53], v[2:3], off offset:64
	global_load_dwordx4 v[54:57], v[4:5], off offset:64
	ds_read_b128 v[58:61], v0 offset:64
	s_waitcnt vmcnt(1) lgkmcnt(0)
	v_mfma_f32_16x16x32_bf16 v[18:21], v[58:61], v[50:53], v[18:21]
	s_waitcnt vmcnt(0)
	v_mfma_f32_16x16x32_bf16 v[14:17], v[58:61], v[54:57], v[14:17]
	ds_read_b128 v[58:61], v0 offset:4416
	s_waitcnt lgkmcnt(0)
	v_mfma_f32_16x16x32_bf16 v[26:29], v[58:61], v[50:53], v[26:29]
	v_mfma_f32_16x16x32_bf16 v[22:25], v[58:61], v[54:57], v[22:25]
	ds_read_b128 v[58:61], v0 offset:8768
	s_waitcnt lgkmcnt(0)
	v_mfma_f32_16x16x32_bf16 v[46:49], v[58:61], v[50:53], v[46:49]
	v_mfma_f32_16x16x32_bf16 v[30:33], v[58:61], v[54:57], v[30:33]
	ds_read_b128 v[58:61], v0 offset:13120
	s_waitcnt lgkmcnt(0)
	v_mfma_f32_16x16x32_bf16 v[6:9], v[58:61], v[50:53], v[6:9]
	v_mfma_f32_16x16x32_bf16 v[10:13], v[58:61], v[54:57], v[10:13]
	global_load_dwordx4 v[50:53], v[2:3], off offset:128
	global_load_dwordx4 v[54:57], v[4:5], off offset:128
	ds_read_b128 v[58:61], v0 offset:128
	s_waitcnt vmcnt(1) lgkmcnt(0)
	v_mfma_f32_16x16x32_bf16 v[18:21], v[58:61], v[50:53], v[18:21]
	s_waitcnt vmcnt(0)
	v_mfma_f32_16x16x32_bf16 v[14:17], v[58:61], v[54:57], v[14:17]
	ds_read_b128 v[58:61], v0 offset:4480
	s_waitcnt lgkmcnt(0)
	v_mfma_f32_16x16x32_bf16 v[62:65], v[58:61], v[50:53], v[26:29]
	v_mfma_f32_16x16x32_bf16 v[58:61], v[58:61], v[54:57], v[22:25]
	s_nop 2
	ds_read_b128 v[22:25], v0 offset:8832
	s_waitcnt lgkmcnt(0)
	v_mfma_f32_16x16x32_bf16 v[46:49], v[22:25], v[50:53], v[46:49]
	v_mfma_f32_16x16x32_bf16 v[66:69], v[22:25], v[54:57], v[30:33]
	ds_read_b128 v[22:25], v0 offset:13184
	s_waitcnt lgkmcnt(0)
	v_mfma_f32_16x16x32_bf16 v[6:9], v[22:25], v[50:53], v[6:9]
	v_mfma_f32_16x16x32_bf16 v[50:53], v[22:25], v[54:57], v[10:13]
	global_load_dwordx4 v[54:57], v[2:3], off offset:192
	s_nop 0
	global_load_dwordx4 v[2:5], v[4:5], off offset:192
	ds_read_b128 v[10:13], v0 offset:192
	s_waitcnt vmcnt(1) lgkmcnt(0)
	v_mfma_f32_16x16x32_bf16 v[30:33], v[10:13], v[54:57], v[18:21]
	s_waitcnt vmcnt(0)
	v_mfma_f32_16x16x32_bf16 v[26:29], v[10:13], v[2:5], v[14:17]
	ds_read_b128 v[10:13], v0 offset:4544
	s_waitcnt lgkmcnt(0)
	v_mfma_f32_16x16x32_bf16 v[22:25], v[10:13], v[54:57], v[62:65]
	v_mfma_f32_16x16x32_bf16 v[18:21], v[10:13], v[2:5], v[58:61]
	ds_read_b128 v[10:13], v0 offset:8896
	s_waitcnt lgkmcnt(0)
	v_mfma_f32_16x16x32_bf16 v[14:17], v[10:13], v[54:57], v[46:49]
	s_nop 2
	ds_read_b128 v[46:49], v0 offset:13248
	s_load_dwordx2 s[4:5], s[12:13], s4 offset:0x0
	v_mfma_f32_16x16x32_bf16 v[10:13], v[10:13], v[2:5], v[66:69]
	s_waitcnt lgkmcnt(0)
	v_mfma_f32_16x16x32_bf16 v[6:9], v[46:49], v[54:57], v[6:9]
	v_mfma_f32_16x16x32_bf16 v[2:5], v[46:49], v[2:5], v[50:53]
	v_lshlrev_b64 v[46:47], 2, v[42:43]
	v_lshl_add_u64 v[42:43], s[4:5], 0, v[46:47]
	s_movk_i32 s4, 0x60
	global_load_dword v37, v[42:43], off
	s_load_dwordx2 s[4:5], s[12:13], s4 offset:0x0
	s_waitcnt lgkmcnt(0)
	v_lshl_add_u64 v[42:43], s[4:5], 0, v[46:47]
	s_movk_i32 s4, 0x68
	global_load_dword v42, v[42:43], off
	s_load_dwordx2 s[4:5], s[12:13], s4 offset:0x0
	s_waitcnt lgkmcnt(0)
	v_lshl_add_u64 v[46:47], s[4:5], 0, v[46:47]
	global_load_dword v0, v[46:47], off
	s_mov_b32 s4, 0x3f2aaaab
	s_mov_b32 s5, 0xf800000
	s_waitcnt vmcnt(2)
	v_add_f32_e32 v30, v30, v37
	v_mul_f32_e32 v30, 0xbfb8aa3b, v30
	v_exp_f32_e32 v30, v30
	v_add_f32_e32 v22, v22, v37
	v_mul_f32_e32 v22, 0xbfb8aa3b, v22
	v_exp_f32_e32 v22, v22
	v_add_f32_e32 v30, 1.0, v30
	v_rcp_f32_e32 v30, v30
	v_add_f32_e32 v23, v23, v37
	s_waitcnt vmcnt(1)
	v_add_f32_e32 v26, v26, v42
	v_mul_f32_e32 v26, 0xbfb8aa3b, v26
	v_mul_f32_e32 v30, 0xc1000000, v30
	v_exp_f32_e32 v26, v26
	v_add_f32_e32 v27, v27, v42
	v_mul_f32_e32 v27, 0xbfb8aa3b, v27
	v_exp_f32_e32 v27, v27
	v_add_f32_e32 v26, 1.0, v26
	s_waitcnt vmcnt(0)
	v_mul_f32_e32 v0, 0xbfb8aa3b, v0
	v_exp_f32_e32 v0, v0
	v_rcp_f32_e32 v26, v26
	v_add_f32_e32 v27, 1.0, v27
	v_rcp_f32_e32 v27, v27
	v_add_f32_e32 v43, 1.0, v0
	v_add_f32_e32 v45, -1.0, v43
	v_sub_f32_e32 v46, v45, v43
	v_add_f32_e32 v46, 1.0, v46
	v_sub_f32_e32 v45, v0, v45
	v_add_f32_e32 v45, v45, v46
	v_frexp_mant_f32_e32 v46, v43
	v_cmp_gt_f32_e32 vcc, s4, v46
	v_cvt_f64_f32_e32 v[46:47], v43
	v_frexp_exp_i32_f64_e32 v46, v[46:47]
	v_subbrev_co_u32_e32 v46, vcc, 0, v46, vcc
	v_sub_u32_e32 v47, 0, v46
	v_ldexp_f32 v43, v43, v47
	v_ldexp_f32 v45, v45, v47
	v_add_f32_e32 v47, -1.0, v43
	v_add_f32_e32 v48, 1.0, v47
	v_sub_f32_e32 v48, v43, v48
	v_add_f32_e32 v48, v45, v48
	v_add_f32_e32 v49, v47, v48
	v_sub_f32_e32 v47, v49, v47
	v_sub_f32_e32 v47, v48, v47
	v_add_f32_e32 v48, 1.0, v43
	v_add_f32_e32 v50, -1.0, v48
	v_sub_f32_e32 v43, v43, v50
	v_add_f32_e32 v43, v45, v43
	v_add_f32_e32 v45, v48, v43
	v_sub_f32_e32 v48, v45, v48
	v_sub_f32_e32 v43, v43, v48
	v_rcp_f32_e32 v48, v45
	v_cvt_f32_i32_e32 v46, v46
	s_mov_b32 s4, 0x3f317218
	v_add_f32_e32 v28, v28, v42
	v_mul_f32_e32 v50, v49, v48
	v_mul_f32_e32 v51, v45, v50
	v_fma_f32 v52, v50, v45, -v51
	v_fmac_f32_e32 v52, v50, v43
	v_add_f32_e32 v53, v51, v52
	v_sub_f32_e32 v54, v49, v53
	v_sub_f32_e32 v49, v49, v54
	v_sub_f32_e32 v51, v53, v51
	v_sub_f32_e32 v49, v49, v53
	v_add_f32_e32 v47, v47, v49
	v_sub_f32_e32 v49, v51, v52
	v_add_f32_e32 v47, v49, v47
	v_add_f32_e32 v49, v54, v47
	v_mul_f32_e32 v51, v48, v49
	v_mul_f32_e32 v52, v45, v51
	v_fma_f32 v45, v51, v45, -v52
	v_fmac_f32_e32 v45, v51, v43
	v_sub_f32_e32 v43, v54, v49
	v_add_f32_e32 v43, v47, v43
	v_add_f32_e32 v47, v52, v45
	v_sub_f32_e32 v53, v49, v47
	v_sub_f32_e32 v49, v49, v53
	v_sub_f32_e32 v52, v47, v52
	v_sub_f32_e32 v47, v49, v47
	v_add_f32_e32 v43, v43, v47
	v_sub_f32_e32 v45, v52, v45
	v_add_f32_e32 v43, v45, v43
	v_add_f32_e32 v45, v50, v51
	v_add_f32_e32 v43, v53, v43
	v_sub_f32_e32 v47, v45, v50
	v_mul_f32_e32 v43, v48, v43
	v_sub_f32_e32 v47, v51, v47
	v_add_f32_e32 v43, v47, v43
	v_mul_f32_e32 v50, 0x3f317218, v46
	v_add_f32_e32 v47, v45, v43
	v_fma_f32 v51, v46, s4, -v50
	v_mul_f32_e32 v48, v47, v47
	v_fmac_f32_e32 v51, 0xb102e308, v46
	v_sub_f32_e32 v45, v47, v45
	v_fmamk_f32 v49, v48, 0x3e9b6dac, v195
	v_sub_f32_e32 v43, v43, v45
	v_add_f32_e32 v45, v50, v51
	v_fmaak_f32 v49, v48, v49, 0x3f2aaada
	v_sub_f32_e32 v46, v45, v50
	v_ldexp_f32 v50, v47, 1
	v_mul_f32_e32 v47, v47, v48
	v_mul_f32_e32 v47, v47, v49
	v_add_f32_e32 v48, v50, v47
	v_sub_f32_e32 v49, v48, v50
	v_ldexp_f32 v43, v43, 1
	v_sub_f32_e32 v47, v47, v49
	v_add_f32_e32 v43, v43, v47
	v_add_f32_e32 v47, v48, v43
	v_sub_f32_e32 v48, v47, v48
	v_sub_f32_e32 v43, v43, v48
	v_add_f32_e32 v48, v45, v47
	v_sub_f32_e32 v49, v48, v45
	v_sub_f32_e32 v50, v48, v49
	v_sub_f32_e32 v46, v51, v46
	v_sub_f32_e32 v45, v45, v50
	v_sub_f32_e32 v47, v47, v49
	v_add_f32_e32 v45, v47, v45
	v_add_f32_e32 v47, v46, v43
	v_sub_f32_e32 v49, v47, v46
	v_sub_f32_e32 v50, v47, v49
	v_sub_f32_e32 v46, v46, v50
	v_sub_f32_e32 v43, v43, v49
	v_add_f32_e32 v45, v47, v45
	v_add_f32_e32 v43, v43, v46
	v_add_f32_e32 v46, v48, v45
	v_sub_f32_e32 v47, v46, v48
	v_sub_f32_e32 v45, v45, v47
	v_add_f32_e32 v43, v43, v45
	s_mov_b32 s4, 0x7f800000
	v_add_f32_e32 v43, v46, v43
	v_cmp_neq_f32_e32 vcc, s4, v0
	s_mov_b32 s4, 0x33800000
	v_mul_f32_e32 v28, 0xbfb8aa3b, v28
	v_cndmask_b32_e32 v43, v198, v43, vcc
	v_cmp_ngt_f32_e32 vcc, -1.0, v0
	v_exp_f32_e32 v28, v28
	v_add_f32_e32 v18, v18, v42
	v_cndmask_b32_e32 v43, v199, v43, vcc
	v_cmp_neq_f32_e32 vcc, -1.0, v0
	v_add_f32_e32 v28, 1.0, v28
	v_rcp_f32_e32 v28, v28
	v_cndmask_b32_e32 v43, v200, v43, vcc
	v_cmp_lt_f32_e64 vcc, |v0|, s4
	s_movk_i32 s4, 0x440
	v_mul_f32_e32 v18, 0xbfb8aa3b, v18
	v_cndmask_b32_e32 v43, v43, v0, vcc
	v_mul_f32_e32 v30, v30, v43
	v_mul_f32_e32 v30, 0x3fb8aa3b, v30
	v_exp_f32_e32 v30, v30
	v_lshl_add_u32 v0, v36, 1, 0
	v_add_f32_e32 v22, 1.0, v22
	v_exp_f32_e32 v18, v18
	v_fma_f32 v45, -v30, v30, 1.0
	v_max_f32_e32 v45, 0, v45
	v_cmp_gt_f32_e32 vcc, s5, v45
	v_mul_f32_e32 v46, 0x4f800000, v45
	v_rcp_f32_e32 v22, v22
	v_cndmask_b32_e32 v45, v45, v46, vcc
	v_sqrt_f32_e32 v46, v45
	v_add_f32_e32 v18, 1.0, v18
	v_mul_f32_e32 v23, 0xbfb8aa3b, v23
	v_exp_f32_e32 v23, v23
	v_add_u32_e32 v47, -1, v46
	v_fma_f32 v48, -v47, v46, v45
	v_cmp_ge_f32_e64 s[10:11], 0, v48
	v_add_u32_e32 v48, 1, v46
	v_add_f32_e32 v23, 1.0, v23
	v_cndmask_b32_e64 v47, v46, v47, s[10:11]
	v_fma_f32 v46, -v48, v46, v45
	v_cmp_lt_f32_e64 s[10:11], 0, v46
	v_rcp_f32_e32 v23, v23
	v_add_f32_e32 v19, v19, v42
	v_cndmask_b32_e64 v46, v47, v48, s[10:11]
	v_mul_f32_e32 v47, 0x37800000, v46
	v_cndmask_b32_e32 v46, v46, v47, vcc
	v_cmp_class_f32_e32 vcc, v45, v196
	v_mul_f32_e32 v23, 0xc1000000, v23
	v_mul_f32_e32 v23, v23, v43
	v_cndmask_b32_e32 v45, v46, v45, vcc
	v_mad_u32_u24 v46, v44, s4, v0
	ds_read_u16 v46, v46
	s_movk_i32 s4, 0x204
	v_mad_u32_u24 v47, v44, s4, v36
	v_mul_f32_e32 v26, v26, v45
	v_lshl_add_u32 v47, v47, 2, 0
	s_waitcnt lgkmcnt(0)
	v_lshlrev_b32_e32 v46, 16, v46
	v_mul_f32_e32 v26, v26, v46
	ds_write2st64_b32 v47, v30, v26 offset0:68 offset1:197
	v_add_f32_e32 v26, v31, v37
	v_mul_f32_e32 v26, 0xbfb8aa3b, v26
	v_exp_f32_e32 v26, v26
	v_lshl_or_b32 v30, v44, 2, 1
	s_movk_i32 s4, 0x81
	v_mul_f32_e32 v23, 0x3fb8aa3b, v23
	v_add_f32_e32 v26, 1.0, v26
	v_rcp_f32_e32 v26, v26
	v_exp_f32_e32 v23, v23
	v_mul_f32_e32 v19, 0xbfb8aa3b, v19
	v_exp_f32_e32 v19, v19
	v_mul_f32_e32 v26, 0xc1000000, v26
	v_mul_f32_e32 v26, v26, v43
	v_mul_f32_e32 v26, 0x3fb8aa3b, v26
	v_exp_f32_e32 v31, v26
	v_add_f32_e32 v19, 1.0, v19
	v_rcp_f32_e32 v19, v19
	v_add_f32_e32 v20, v20, v42
	v_fma_f32 v26, -v31, v31, 1.0
	v_max_f32_e32 v26, 0, v26
	v_cmp_gt_f32_e32 vcc, s5, v26
	v_mul_f32_e32 v44, 0x4f800000, v26
	v_mul_f32_e32 v20, 0xbfb8aa3b, v20
	v_cndmask_b32_e32 v26, v26, v44, vcc
	v_sqrt_f32_e32 v44, v26
	v_exp_f32_e32 v20, v20
	v_add_f32_e32 v21, v21, v42
	v_mul_f32_e32 v21, 0xbfb8aa3b, v21
	v_add_u32_e32 v45, -1, v44
	v_fma_f32 v46, -v45, v44, v26
	v_cmp_ge_f32_e64 s[10:11], 0, v46
	v_add_u32_e32 v46, 1, v44
	v_add_f32_e32 v20, 1.0, v20
	v_cndmask_b32_e64 v45, v44, v45, s[10:11]
	v_fma_f32 v44, -v46, v44, v26
	v_cmp_lt_f32_e64 s[10:11], 0, v44
	v_rcp_f32_e32 v20, v20
	v_exp_f32_e32 v21, v21
	v_cndmask_b32_e64 v44, v45, v46, s[10:11]
	v_mul_f32_e32 v45, 0x37800000, v44
	v_cndmask_b32_e32 v44, v44, v45, vcc
	v_cmp_class_f32_e32 vcc, v26, v196
	v_add_f32_e32 v14, v14, v37
	v_mul_f32_e32 v14, 0xbfb8aa3b, v14
	v_cndmask_b32_e32 v44, v44, v26, vcc
	v_mad_u32_u24 v26, v30, s18, v0
	ds_read_u16 v0, v26
	v_mul_f32_e32 v27, v27, v44
	v_exp_f32_e32 v14, v14
	v_add_f32_e32 v21, 1.0, v21
	v_add_f32_e32 v10, v10, v42
	s_waitcnt lgkmcnt(0)
	v_lshlrev_b32_e32 v45, 16, v0
	v_mad_u32_u24 v0, v30, s4, v36
	v_add_f32_e32 v30, v32, v37
	v_mul_f32_e32 v30, 0xbfb8aa3b, v30
	v_exp_f32_e32 v30, v30
	v_mul_f32_e32 v27, v27, v45
	v_lshl_add_u32 v0, v0, 2, 0
	v_rcp_f32_e32 v21, v21
	v_add_f32_e32 v30, 1.0, v30
	v_rcp_f32_e32 v30, v30
	v_mul_f32_e32 v10, 0xbfb8aa3b, v10
	v_add_f32_e32 v14, 1.0, v14
	v_exp_f32_e32 v10, v10
	v_mul_f32_e32 v30, 0xc1000000, v30
	v_mul_f32_e32 v30, v30, v43
	v_mul_f32_e32 v30, 0x3fb8aa3b, v30
	v_exp_f32_e32 v30, v30
	v_rcp_f32_e32 v14, v14
	v_add_f32_e32 v10, 1.0, v10
	v_add_f32_e32 v15, v15, v37
	v_fma_f32 v32, -v30, v30, 1.0
	v_max_f32_e32 v32, 0, v32
	v_cmp_gt_f32_e32 vcc, s5, v32
	v_mul_f32_e32 v36, 0x4f800000, v32
	v_mul_f32_e32 v15, 0xbfb8aa3b, v15
	v_cndmask_b32_e32 v32, v32, v36, vcc
	v_sqrt_f32_e32 v36, v32
	v_exp_f32_e32 v15, v15
	v_add_f32_e32 v11, v11, v42
	v_mul_f32_e32 v11, 0xbfb8aa3b, v11
	v_add_u32_e32 v44, -1, v36
	v_fma_f32 v45, -v44, v36, v32
	v_cmp_ge_f32_e64 s[10:11], 0, v45
	v_add_u32_e32 v45, 1, v36
	v_add_f32_e32 v15, 1.0, v15
	v_cndmask_b32_e64 v44, v36, v44, s[10:11]
	v_fma_f32 v36, -v45, v36, v32
	v_cmp_lt_f32_e64 s[10:11], 0, v36
	v_rcp_f32_e32 v15, v15
	v_exp_f32_e32 v11, v11
	v_cndmask_b32_e64 v36, v44, v45, s[10:11]
	v_mul_f32_e32 v44, 0x37800000, v36
	v_cndmask_b32_e32 v36, v36, v44, vcc
	v_cmp_class_f32_e32 vcc, v32, v196
	v_add_u32_e32 v44, 0x4400, v0
	ds_write2_b32 v44, v31, v30 offset1:129
	v_cndmask_b32_e32 v32, v36, v32, vcc
	ds_read_u16 v36, v26 offset:272
	v_mul_f32_e32 v28, v28, v32
	v_add_u32_e32 v30, 0xc400, v0
	v_mul_f32_e32 v15, 0xc1000000, v15
	v_mul_f32_e32 v15, v15, v43
	s_waitcnt lgkmcnt(0)
	v_lshlrev_b32_e32 v36, 16, v36
	v_mul_f32_e32 v28, v28, v36
	ds_write2_b32 v30, v27, v28 offset0:64 offset1:193
	v_add_f32_e32 v27, v33, v37
	v_mul_f32_e32 v27, 0xbfb8aa3b, v27
	v_exp_f32_e32 v27, v27
	v_add_f32_e32 v28, v29, v42
	v_mul_f32_e32 v28, 0xbfb8aa3b, v28
	v_exp_f32_e32 v28, v28
	v_add_f32_e32 v27, 1.0, v27
	v_rcp_f32_e32 v27, v27
	v_mul_f32_e32 v15, 0x3fb8aa3b, v15
	v_add_f32_e32 v28, 1.0, v28
	v_rcp_f32_e32 v28, v28
	v_mul_f32_e32 v27, 0xc1000000, v27
	v_mul_f32_e32 v27, v27, v43
	v_mul_f32_e32 v27, 0x3fb8aa3b, v27
	v_exp_f32_e32 v27, v27
	v_exp_f32_e32 v15, v15
	v_add_f32_e32 v11, 1.0, v11
	v_rcp_f32_e32 v11, v11
	v_fma_f32 v29, -v27, v27, 1.0
	v_max_f32_e32 v29, 0, v29
	v_cmp_gt_f32_e32 vcc, s5, v29
	v_mul_f32_e32 v30, 0x4f800000, v29
	ds_write_b32 v0, v27 offset:18440
	v_cndmask_b32_e32 v29, v29, v30, vcc
	v_sqrt_f32_e32 v30, v29
	v_add_f32_e32 v12, v12, v42
	v_mul_f32_e32 v12, 0xbfb8aa3b, v12
	v_exp_f32_e32 v12, v12
	v_add_u32_e32 v31, -1, v30
	v_fma_f32 v32, -v31, v30, v29
	v_cmp_ge_f32_e64 s[10:11], 0, v32
	v_add_u32_e32 v32, 1, v30
	v_add_f32_e32 v12, 1.0, v12
	v_cndmask_b32_e64 v31, v30, v31, s[10:11]
	v_fma_f32 v30, -v32, v30, v29
	v_cmp_lt_f32_e64 s[10:11], 0, v30
	v_rcp_f32_e32 v12, v12
	v_add_f32_e32 v6, v6, v37
	v_cndmask_b32_e64 v30, v31, v32, s[10:11]
	v_mul_f32_e32 v31, 0x37800000, v30
	v_cndmask_b32_e32 v30, v30, v31, vcc
	v_cmp_class_f32_e32 vcc, v29, v196
	v_mul_f32_e32 v6, 0xbfb8aa3b, v6
	v_exp_f32_e32 v6, v6
	v_cndmask_b32_e32 v29, v30, v29, vcc
	ds_read_u16 v30, v26 offset:544
	v_mul_f32_e32 v27, v28, v29
	v_add_f32_e32 v6, 1.0, v6
	v_rcp_f32_e32 v6, v6
	v_add_f32_e32 v2, v2, v42
	s_waitcnt lgkmcnt(0)
	v_lshlrev_b32_e32 v30, 16, v30
	v_mul_f32_e32 v27, v27, v30
	ds_write_b32 v0, v27 offset:51464
	v_rcp_f32_e32 v27, v18
	v_mul_f32_e32 v18, 0xc1000000, v22
	v_mul_f32_e32 v18, v18, v43
	v_mul_f32_e32 v18, 0x3fb8aa3b, v18
	v_exp_f32_e32 v22, v18
	v_mul_f32_e32 v6, 0xc1000000, v6
	v_mul_f32_e32 v6, v6, v43
	v_mul_f32_e32 v6, 0x3fb8aa3b, v6
	v_fma_f32 v18, -v22, v22, 1.0
	v_max_f32_e32 v18, 0, v18
	v_cmp_gt_f32_e32 vcc, s5, v18
	v_mul_f32_e32 v28, 0x4f800000, v18
	v_exp_f32_e32 v6, v6
	v_cndmask_b32_e32 v18, v18, v28, vcc
	v_sqrt_f32_e32 v28, v18
	v_mul_f32_e32 v2, 0xbfb8aa3b, v2
	v_exp_f32_e32 v2, v2
	v_add_f32_e32 v3, v3, v42
	v_add_u32_e32 v29, -1, v28
	v_fma_f32 v30, -v29, v28, v18
	v_cmp_ge_f32_e64 s[10:11], 0, v30
	v_add_u32_e32 v30, 1, v28
	v_add_f32_e32 v2, 1.0, v2
	v_cndmask_b32_e64 v29, v28, v29, s[10:11]
	v_fma_f32 v28, -v30, v28, v18
	v_cmp_lt_f32_e64 s[10:11], 0, v28
	v_rcp_f32_e32 v2, v2
	v_mul_f32_e32 v3, 0xbfb8aa3b, v3
	v_cndmask_b32_e64 v28, v29, v30, s[10:11]
	v_mul_f32_e32 v29, 0x37800000, v28
	v_cndmask_b32_e32 v28, v28, v29, vcc
	v_cmp_class_f32_e32 vcc, v18, v196
	v_exp_f32_e32 v3, v3
	v_add_f32_e32 v4, v4, v42
	v_cndmask_b32_e32 v28, v28, v18, vcc
	ds_read_u16 v18, v26 offset:4080
	v_mul_f32_e32 v27, v27, v28
	v_fma_f32 v28, -v23, v23, 1.0
	v_max_f32_e32 v28, 0, v28
	v_cmp_gt_f32_e32 vcc, s5, v28
	s_waitcnt lgkmcnt(0)
	v_lshlrev_b32_e32 v29, 16, v18
	v_mul_f32_e32 v27, v27, v29
	v_mul_f32_e32 v29, 0x4f800000, v28
	v_cndmask_b32_e32 v28, v28, v29, vcc
	v_sqrt_f32_e32 v29, v28
	v_add_u32_e32 v18, 0x1e3c, v0
	v_add_f32_e32 v3, 1.0, v3
	v_rcp_f32_e32 v3, v3
	v_add_u32_e32 v30, -1, v29
	v_fma_f32 v31, -v30, v29, v28
	v_cmp_ge_f32_e64 s[10:11], 0, v31
	v_add_u32_e32 v31, 1, v29
	v_mul_f32_e32 v4, 0xbfb8aa3b, v4
	v_cndmask_b32_e64 v30, v29, v30, s[10:11]
	v_fma_f32 v29, -v31, v29, v28
	v_cmp_lt_f32_e64 s[10:11], 0, v29
	v_exp_f32_e32 v4, v4
	s_movk_i32 s4, 0x80
	v_cndmask_b32_e64 v29, v30, v31, s[10:11]
	v_mul_f32_e32 v30, 0x37800000, v29
	v_cndmask_b32_e32 v29, v29, v30, vcc
	v_cmp_class_f32_e32 vcc, v28, v196
	v_add_u32_e32 v30, 0x6200, v0
	ds_write2_b32 v30, v22, v23 offset0:15 offset1:144
	v_cndmask_b32_e32 v28, v29, v28, vcc
	ds_read_u16 v29, v26 offset:4352
	v_mul_f32_e32 v19, v19, v28
	v_add_u32_e32 v22, 0xe200, v0
	v_add_f32_e32 v4, 1.0, v4
	v_rcp_f32_e32 v4, v4
	s_waitcnt lgkmcnt(0)
	v_lshlrev_b32_e32 v29, 16, v29
	v_mul_f32_e32 v19, v19, v29
	ds_write2_b32 v22, v27, v19 offset0:79 offset1:208
	v_add_f32_e32 v19, v24, v37
	v_mul_f32_e32 v19, 0xbfb8aa3b, v19
	v_exp_f32_e32 v19, v19
	s_nop 0
	v_add_f32_e32 v19, 1.0, v19
	v_rcp_f32_e32 v19, v19
	s_nop 0
	v_mul_f32_e32 v19, 0xc1000000, v19
	v_mul_f32_e32 v19, v19, v43
	v_mul_f32_e32 v19, 0x3fb8aa3b, v19
	v_exp_f32_e32 v19, v19
	s_nop 0
	v_fma_f32 v22, -v19, v19, 1.0
	v_max_f32_e32 v22, 0, v22
	v_cmp_gt_f32_e32 vcc, s5, v22
	v_mul_f32_e32 v23, 0x4f800000, v22
	s_nop 0
	v_cndmask_b32_e32 v22, v22, v23, vcc
	v_sqrt_f32_e32 v23, v22
	s_nop 0
	v_add_u32_e32 v24, -1, v23
	v_fma_f32 v27, -v24, v23, v22
	v_cmp_ge_f32_e64 s[10:11], 0, v27
	v_add_u32_e32 v27, 1, v23
	s_nop 0
	v_cndmask_b32_e64 v24, v23, v24, s[10:11]
	v_fma_f32 v23, -v27, v23, v22
	v_cmp_lt_f32_e64 s[10:11], 0, v23
	s_nop 1
	v_cndmask_b32_e64 v23, v24, v27, s[10:11]
	v_mul_f32_e32 v24, 0x37800000, v23
	v_cndmask_b32_e32 v23, v23, v24, vcc
	v_cmp_class_f32_e32 vcc, v22, v196
	s_nop 1
	v_cndmask_b32_e32 v22, v23, v22, vcc
	v_mul_f32_e32 v20, v20, v22
	v_add_f32_e32 v22, v25, v37
	v_mul_f32_e32 v22, 0xbfb8aa3b, v22
	v_exp_f32_e32 v22, v22
	ds_read_u16 v23, v26 offset:4624
	v_add_f32_e32 v22, 1.0, v22
	v_rcp_f32_e32 v22, v22
	s_waitcnt lgkmcnt(0)
	v_lshlrev_b32_e32 v23, 16, v23
	v_mul_f32_e32 v20, v20, v23
	v_mul_f32_e32 v22, 0xc1000000, v22
	v_mul_f32_e32 v22, v22, v43
	v_mul_f32_e32 v22, 0x3fb8aa3b, v22
	v_exp_f32_e32 v22, v22
	s_nop 0
	v_fma_f32 v23, -v22, v22, 1.0
	v_max_f32_e32 v23, 0, v23
	v_cmp_gt_f32_e32 vcc, s5, v23
	v_mul_f32_e32 v24, 0x4f800000, v23
	s_nop 0
	v_cndmask_b32_e32 v23, v23, v24, vcc
	v_sqrt_f32_e32 v24, v23
	s_nop 0
	v_add_u32_e32 v25, -1, v24
	v_fma_f32 v27, -v25, v24, v23
	v_cmp_ge_f32_e64 s[10:11], 0, v27
	v_add_u32_e32 v27, 1, v24
	s_nop 0
	v_cndmask_b32_e64 v25, v24, v25, s[10:11]
	v_fma_f32 v24, -v27, v24, v23
	v_cmp_lt_f32_e64 s[10:11], 0, v24
	s_nop 1
	v_cndmask_b32_e64 v24, v25, v27, s[10:11]
	v_mul_f32_e32 v25, 0x37800000, v24
	v_cndmask_b32_e32 v24, v24, v25, vcc
	v_cmp_class_f32_e32 vcc, v23, v196
	v_add_u32_e32 v25, 0x6600, v0
	ds_write2_b32 v25, v19, v22 offset0:17 offset1:146
	v_cndmask_b32_e32 v23, v24, v23, vcc
	ds_read_u16 v24, v26 offset:4896
	v_mul_f32_e32 v19, v21, v23
	v_add_u32_e32 v21, 0xe600, v0
	s_waitcnt lgkmcnt(0)
	v_lshlrev_b32_e32 v24, 16, v24
	v_mul_f32_e32 v19, v19, v24
	ds_write2_b32 v21, v20, v19 offset0:81 offset1:210
	v_rcp_f32_e32 v19, v10
	v_mul_f32_e32 v10, 0xc1000000, v14
	v_mul_f32_e32 v10, v10, v43
	v_mul_f32_e32 v10, 0x3fb8aa3b, v10
	v_exp_f32_e32 v14, v10
	s_nop 0
	v_fma_f32 v10, -v14, v14, 1.0
	v_max_f32_e32 v10, 0, v10
	v_cmp_gt_f32_e32 vcc, s5, v10
	v_mul_f32_e32 v20, 0x4f800000, v10
	s_nop 0
	v_cndmask_b32_e32 v10, v10, v20, vcc
	v_sqrt_f32_e32 v20, v10
	s_nop 0
	v_add_u32_e32 v21, -1, v20
	v_fma_f32 v22, -v21, v20, v10
	v_cmp_ge_f32_e64 s[10:11], 0, v22
	v_add_u32_e32 v22, 1, v20
	s_nop 0
	v_cndmask_b32_e64 v21, v20, v21, s[10:11]
	v_fma_f32 v20, -v22, v20, v10
	v_cmp_lt_f32_e64 s[10:11], 0, v20
	s_nop 1
	v_cndmask_b32_e64 v20, v21, v22, s[10:11]
	v_mul_f32_e32 v21, 0x37800000, v20
	v_cndmask_b32_e32 v20, v20, v21, vcc
	v_cmp_class_f32_e32 vcc, v10, v196
	s_nop 1
	v_cndmask_b32_e32 v20, v20, v10, vcc
	ds_read_u16 v10, v26 offset:8432
	v_mul_f32_e32 v19, v19, v20
	v_add_u32_e32 v20, 0x1037c, v0
	s_waitcnt lgkmcnt(0)
	v_lshlrev_b32_e32 v21, 16, v10
	v_mul_f32_e32 v19, v19, v21
	ds_write_b32 v20, v19
	v_fma_f32 v19, -v15, v15, 1.0
	v_max_f32_e32 v19, 0, v19
	v_cmp_gt_f32_e32 vcc, s5, v19
	v_mul_f32_e32 v20, 0x4f800000, v19
	v_add_u32_e32 v10, 0x3e7c, v0
	v_cndmask_b32_e32 v19, v19, v20, vcc
	v_sqrt_f32_e32 v20, v19
	s_nop 0
	v_add_u32_e32 v21, -1, v20
	v_fma_f32 v22, -v21, v20, v19
	v_cmp_ge_f32_e64 s[10:11], 0, v22
	v_add_u32_e32 v22, 1, v20
	s_nop 0
	v_cndmask_b32_e64 v21, v20, v21, s[10:11]
	v_fma_f32 v20, -v22, v20, v19
	v_cmp_lt_f32_e64 s[10:11], 0, v20
	s_nop 1
	v_cndmask_b32_e64 v20, v21, v22, s[10:11]
	v_mul_f32_e32 v21, 0x37800000, v20
	v_cndmask_b32_e32 v20, v20, v21, vcc
	v_add_u32_e32 v21, 0x8200, v0
	ds_write2_b32 v21, v14, v15 offset0:31 offset1:160
	v_add_f32_e32 v14, v16, v37
	v_mul_f32_e32 v14, 0xbfb8aa3b, v14
	v_exp_f32_e32 v14, v14
	v_cmp_class_f32_e32 vcc, v19, v196
	v_add_f32_e32 v14, 1.0, v14
	v_rcp_f32_e32 v14, v14
	v_cndmask_b32_e32 v19, v20, v19, vcc
	ds_read_u16 v20, v26 offset:8704
	v_mul_f32_e32 v11, v11, v19
	v_mul_f32_e32 v14, 0xc1000000, v14
	v_mul_f32_e32 v14, v14, v43
	v_mul_f32_e32 v14, 0x3fb8aa3b, v14
	v_exp_f32_e32 v14, v14
	s_waitcnt lgkmcnt(0)
	v_lshlrev_b32_e32 v20, 16, v20
	v_mul_f32_e32 v11, v11, v20
	v_fma_f32 v15, -v14, v14, 1.0
	v_max_f32_e32 v15, 0, v15
	v_cmp_gt_f32_e32 vcc, s5, v15
	v_mul_f32_e32 v16, 0x4f800000, v15
	s_nop 0
	v_cndmask_b32_e32 v15, v15, v16, vcc
	v_sqrt_f32_e32 v16, v15
	s_nop 0
	v_add_u32_e32 v19, -1, v16
	v_fma_f32 v20, -v19, v16, v15
	v_cmp_ge_f32_e64 s[10:11], 0, v20
	v_add_u32_e32 v20, 1, v16
	s_nop 0
	v_cndmask_b32_e64 v19, v16, v19, s[10:11]
	v_fma_f32 v16, -v20, v16, v15
	v_cmp_lt_f32_e64 s[10:11], 0, v16
	s_nop 1
	v_cndmask_b32_e64 v16, v19, v20, s[10:11]
	v_mul_f32_e32 v19, 0x37800000, v16
	v_cndmask_b32_e32 v16, v16, v19, vcc
	v_cmp_class_f32_e32 vcc, v15, v196
	s_nop 1
	v_cndmask_b32_e32 v15, v16, v15, vcc
	ds_read_u16 v16, v26 offset:8976
	v_mul_f32_e32 v12, v12, v15
	v_add_u32_e32 v15, 0xe600, v18
	s_waitcnt lgkmcnt(0)
	v_lshlrev_b32_e32 v16, 16, v16
	v_mul_f32_e32 v12, v12, v16
	ds_write2_b32 v15, v11, v12 offset0:81 offset1:210
	v_add_f32_e32 v11, v17, v37
	v_mul_f32_e32 v11, 0xbfb8aa3b, v11
	v_exp_f32_e32 v11, v11
	v_add_f32_e32 v12, v13, v42
	v_mul_f32_e32 v12, 0xbfb8aa3b, v12
	v_exp_f32_e32 v12, v12
	v_add_f32_e32 v11, 1.0, v11
	v_rcp_f32_e32 v11, v11
	v_add_f32_e32 v12, 1.0, v12
	v_rcp_f32_e32 v12, v12
	v_mul_f32_e32 v11, 0xc1000000, v11
	v_mul_f32_e32 v11, v11, v43
	v_mul_f32_e32 v11, 0x3fb8aa3b, v11
	v_exp_f32_e32 v11, v11
	s_nop 0
	v_fma_f32 v13, -v11, v11, 1.0
	v_max_f32_e32 v13, 0, v13
	v_cmp_gt_f32_e32 vcc, s5, v13
	v_mul_f32_e32 v15, 0x4f800000, v13
	s_nop 0
	v_cndmask_b32_e32 v13, v13, v15, vcc
	v_sqrt_f32_e32 v15, v13
	s_nop 0
	v_add_u32_e32 v16, -1, v15
	v_fma_f32 v17, -v16, v15, v13
	v_cmp_ge_f32_e64 s[10:11], 0, v17
	v_add_u32_e32 v17, 1, v15
	s_nop 0
	v_cndmask_b32_e64 v16, v15, v16, s[10:11]
	v_fma_f32 v15, -v17, v15, v13
	v_cmp_lt_f32_e64 s[10:11], 0, v15
	s_nop 1
	v_cndmask_b32_e64 v15, v16, v17, s[10:11]
	v_mul_f32_e32 v16, 0x37800000, v15
	v_cndmask_b32_e32 v15, v15, v16, vcc
	v_cmp_class_f32_e32 vcc, v13, v196
	v_add_u32_e32 v16, 0x8600, v0
	ds_write2_b32 v16, v14, v11 offset0:33 offset1:162
	v_cndmask_b32_e32 v13, v15, v13, vcc
	ds_read_u16 v15, v26 offset:9248
	v_mul_f32_e32 v11, v12, v13
	s_waitcnt lgkmcnt(0)
	v_lshlrev_b32_e32 v15, 16, v15
	v_mul_f32_e32 v11, v11, v15
	ds_write_b32 v18, v11 offset:60236
	v_fma_f32 v11, -v6, v6, 1.0
	v_max_f32_e32 v11, 0, v11
	v_cmp_gt_f32_e32 vcc, s5, v11
	v_mul_f32_e32 v12, 0x4f800000, v11
	s_nop 0
	v_cndmask_b32_e32 v11, v11, v12, vcc
	v_sqrt_f32_e32 v12, v11
	s_nop 0
	v_add_u32_e32 v13, -1, v12
	v_fma_f32 v14, -v13, v12, v11
	v_cmp_ge_f32_e64 s[10:11], 0, v14
	v_add_u32_e32 v14, 1, v12
	s_nop 0
	v_cndmask_b32_e64 v13, v12, v13, s[10:11]
	v_fma_f32 v12, -v14, v12, v11
	v_cmp_lt_f32_e64 s[10:11], 0, v12
	s_nop 1
	v_cndmask_b32_e64 v12, v13, v14, s[10:11]
	v_mul_f32_e32 v13, 0x37800000, v12
	v_cndmask_b32_e32 v12, v12, v13, vcc
	v_cmp_class_f32_e32 vcc, v11, v196
	s_nop 1
	v_cndmask_b32_e32 v11, v12, v11, vcc
	ds_read_u16 v12, v26 offset:12784
	v_mul_f32_e32 v2, v2, v11
	v_add_u32_e32 v11, 0x123bc, v0
	s_waitcnt lgkmcnt(0)
	v_lshlrev_b32_e32 v12, 16, v12
	v_mul_f32_e32 v2, v2, v12
	ds_write_b32 v11, v2
	v_add_f32_e32 v2, v7, v37
	v_mul_f32_e32 v2, 0xbfb8aa3b, v2
	v_exp_f32_e32 v2, v2
	s_nop 0
	v_add_f32_e32 v2, 1.0, v2
	v_rcp_f32_e32 v2, v2
	s_nop 0
	v_mul_f32_e32 v2, 0xc1000000, v2
	v_mul_f32_e32 v2, v2, v43
	v_mul_f32_e32 v2, 0x3fb8aa3b, v2
	v_exp_f32_e32 v2, v2
	s_nop 0
	v_fma_f32 v7, -v2, v2, 1.0
	v_max_f32_e32 v7, 0, v7
	v_cmp_gt_f32_e32 vcc, s5, v7
	v_mul_f32_e32 v11, 0x4f800000, v7
	s_nop 0
	v_cndmask_b32_e32 v7, v7, v11, vcc
	v_sqrt_f32_e32 v11, v7
	s_nop 0
	v_add_u32_e32 v12, -1, v11
	v_fma_f32 v13, -v12, v11, v7
	v_cmp_ge_f32_e64 s[10:11], 0, v13
	v_add_u32_e32 v13, 1, v11
	s_nop 0
	v_cndmask_b32_e64 v12, v11, v12, s[10:11]
	v_fma_f32 v11, -v13, v11, v7
	v_cmp_lt_f32_e64 s[10:11], 0, v11
	s_nop 1
	v_cndmask_b32_e64 v11, v12, v13, s[10:11]
	v_mul_f32_e32 v12, 0x37800000, v11
	v_cndmask_b32_e32 v11, v11, v12, vcc
	v_cmp_class_f32_e32 vcc, v7, v196
	v_add_u32_e32 v12, 0xa200, v0
	ds_write2_b32 v12, v6, v2 offset0:47 offset1:176
	v_cndmask_b32_e32 v7, v11, v7, vcc
	ds_read_u16 v11, v26 offset:13056
	v_mul_f32_e32 v2, v3, v7
	v_add_u32_e32 v0, 0xa600, v0
	s_waitcnt lgkmcnt(0)
	v_lshlrev_b32_e32 v11, 16, v11
	v_mul_f32_e32 v3, v2, v11
	v_add_f32_e32 v2, v8, v37
	v_mul_f32_e32 v2, 0xbfb8aa3b, v2
	v_exp_f32_e32 v2, v2
	s_nop 0
	v_add_f32_e32 v2, 1.0, v2
	v_rcp_f32_e32 v2, v2
	s_nop 0
	v_mul_f32_e32 v2, 0xc1000000, v2
	v_mul_f32_e32 v2, v2, v43
	v_mul_f32_e32 v2, 0x3fb8aa3b, v2
	v_exp_f32_e32 v2, v2
	s_nop 0
	v_fma_f32 v6, -v2, v2, 1.0
	v_max_f32_e32 v6, 0, v6
	v_cmp_gt_f32_e32 vcc, s5, v6
	v_mul_f32_e32 v7, 0x4f800000, v6
	s_nop 0
	v_cndmask_b32_e32 v6, v6, v7, vcc
	v_sqrt_f32_e32 v7, v6
	s_nop 0
	v_add_u32_e32 v8, -1, v7
	v_fma_f32 v11, -v8, v7, v6
	v_cmp_ge_f32_e64 s[10:11], 0, v11
	v_add_u32_e32 v11, 1, v7
	s_nop 0
	v_cndmask_b32_e64 v8, v7, v8, s[10:11]
	v_fma_f32 v7, -v11, v7, v6
	v_cmp_lt_f32_e64 s[10:11], 0, v7
	s_nop 1
	v_cndmask_b32_e64 v7, v8, v11, s[10:11]
	v_mul_f32_e32 v8, 0x37800000, v7
	v_cndmask_b32_e32 v7, v7, v8, vcc
	v_cmp_class_f32_e32 vcc, v6, v196
	s_nop 1
	v_cndmask_b32_e32 v6, v7, v6, vcc
	ds_read_u16 v7, v26 offset:13328
	v_mul_f32_e32 v4, v4, v6
	v_add_u32_e32 v6, 0xe600, v10
	s_waitcnt lgkmcnt(0)
	v_lshlrev_b32_e32 v7, 16, v7
	v_mul_f32_e32 v4, v4, v7
	ds_write2_b32 v6, v3, v4 offset0:81 offset1:210
	v_add_f32_e32 v3, v9, v37
	v_mul_f32_e32 v3, 0xbfb8aa3b, v3
	v_exp_f32_e32 v3, v3
	s_nop 0
	v_add_f32_e32 v3, 1.0, v3
	v_rcp_f32_e32 v4, v3
	v_add_f32_e32 v3, v5, v42
	v_mul_f32_e32 v3, 0xbfb8aa3b, v3
	v_exp_f32_e32 v3, v3
	v_mul_f32_e32 v4, 0xc1000000, v4
	v_mul_f32_e32 v4, v4, v43
	v_mul_f32_e32 v4, 0x3fb8aa3b, v4
	v_exp_f32_e32 v4, v4
	v_add_f32_e32 v3, 1.0, v3
	v_rcp_f32_e32 v3, v3
	v_fma_f32 v5, -v4, v4, 1.0
	v_max_f32_e32 v5, 0, v5
	v_cmp_gt_f32_e32 vcc, s5, v5
	v_mul_f32_e32 v6, 0x4f800000, v5
	ds_write2_b32 v0, v2, v4 offset0:49 offset1:178
	v_cndmask_b32_e32 v5, v5, v6, vcc
	v_sqrt_f32_e32 v6, v5
	s_nop 0
	v_add_u32_e32 v7, -1, v6
	v_fma_f32 v8, -v7, v6, v5
	v_cmp_ge_f32_e64 s[10:11], 0, v8
	v_add_u32_e32 v8, 1, v6
	s_nop 0
	v_cndmask_b32_e64 v7, v6, v7, s[10:11]
	v_fma_f32 v6, -v8, v6, v5
	v_cmp_lt_f32_e64 s[10:11], 0, v6
	s_nop 1
	v_cndmask_b32_e64 v6, v7, v8, s[10:11]
	v_mul_f32_e32 v7, 0x37800000, v6
	v_cndmask_b32_e32 v6, v6, v7, vcc
	v_cmp_class_f32_e32 vcc, v5, v196
	s_nop 1
	v_cndmask_b32_e32 v5, v6, v5, vcc
	ds_read_u16 v6, v26 offset:13600
	v_mul_f32_e32 v0, v3, v5
	v_cmp_gt_i32_e32 vcc, s4, v39
	s_waitcnt lgkmcnt(0)
	v_lshlrev_b32_e32 v6, 16, v6
	v_mul_f32_e32 v0, v0, v6
	ds_write_b32 v10, v0 offset:60236
	s_waitcnt lgkmcnt(0)
	s_barrier
	s_and_saveexec_b64 s[10:11], vcc
	s_cbranch_execz .LBB0_654
	v_readlane_b32 s4, v250, 40
	v_lshl_add_u32 v0, v39, 1, 0
	v_mov_b32_e32 v3, 0
	v_lshl_add_u32 v4, v39, 2, s4
	v_mov_b32_e32 v2, 1.0
	s_movk_i32 s4, 0xbc00
	v_add_u32_e32 v8, 0x14600, v0
	v_add_u32_e32 v5, 0x0, v4
	ds_read2_b32 v[70:71], v5 offset1:129
	v_add_u32_e32 v6, 0x8100, v4
	ds_read2_b32 v[102:103], v6 offset1:129
	v_add_u32_e32 v5, 0x408, v4
	ds_read2_b32 v[72:73], v5 offset1:129
	v_add_u32_e32 v6, 0x8508, v4
	ds_read2_b32 v[104:105], v6 offset1:129
	v_add_u32_e32 v5, 0x810, v4
	ds_read2_b32 v[74:75], v5 offset1:129
	v_add_u32_e32 v6, 0x8910, v4
	ds_read2_b32 v[106:107], v6 offset1:129
	v_add_u32_e32 v5, 0xc18, v4
	ds_read2_b32 v[76:77], v5 offset1:129
	v_add_u32_e32 v6, 0x8d18, v4
	ds_read2_b32 v[108:109], v6 offset1:129
	v_add_u32_e32 v5, 0x1020, v4
	ds_read2_b32 v[78:79], v5 offset1:129
	v_add_u32_e32 v6, 0x9120, v4
	ds_read2_b32 v[110:111], v6 offset1:129
	v_add_u32_e32 v5, 0x1428, v4
	ds_read2_b32 v[80:81], v5 offset1:129
	v_add_u32_e32 v6, 0x9528, v4
	ds_read2_b32 v[112:113], v6 offset1:129
	v_add_u32_e32 v5, 0x1830, v4
	ds_read2_b32 v[82:83], v5 offset1:129
	v_add_u32_e32 v6, 0x9930, v4
	ds_read2_b32 v[114:115], v6 offset1:129
	v_add_u32_e32 v5, 0x1c38, v4
	ds_read2_b32 v[84:85], v5 offset1:129
	v_add_u32_e32 v6, 0x9d38, v4
	ds_read2_b32 v[116:117], v6 offset1:129
	v_add_u32_e32 v5, 0x2040, v4
	ds_read2_b32 v[86:87], v5 offset1:129
	v_add_u32_e32 v6, 0xa140, v4
	ds_read2_b32 v[118:119], v6 offset1:129
	v_add_u32_e32 v5, 0x2448, v4
	ds_read2_b32 v[88:89], v5 offset1:129
	v_add_u32_e32 v6, 0xa548, v4
	ds_read2_b32 v[120:121], v6 offset1:129
	v_add_u32_e32 v5, 0x2850, v4
	ds_read2_b32 v[90:91], v5 offset1:129
	v_add_u32_e32 v6, 0xa950, v4
	ds_read2_b32 v[122:123], v6 offset1:129
	v_add_u32_e32 v5, 0x2c58, v4
	ds_read2_b32 v[92:93], v5 offset1:129
	v_add_u32_e32 v6, 0xad58, v4
	ds_read2_b32 v[124:125], v6 offset1:129
	v_add_u32_e32 v5, 0x3060, v4
	ds_read2_b32 v[94:95], v5 offset1:129
	v_add_u32_e32 v6, 0xb160, v4
	ds_read2_b32 v[126:127], v6 offset1:129
	v_add_u32_e32 v5, 0x3468, v4
	ds_read2_b32 v[96:97], v5 offset1:129
	v_add_u32_e32 v6, 0xb568, v4
	ds_read2_b32 v[128:129], v6 offset1:129
	v_add_u32_e32 v5, 0x3870, v4
	ds_read2_b32 v[98:99], v5 offset1:129
	v_add_u32_e32 v6, 0xb970, v4
	ds_read2_b32 v[130:131], v6 offset1:129
	v_add_u32_e32 v5, 0x3c78, v4
	ds_read2_b32 v[100:101], v5 offset1:129
	v_add_u32_e32 v6, 0xbd78, v4
	ds_read2_b32 v[132:133], v6 offset1:129
	s_waitcnt lgkmcnt(0)
	v_mul_f32_e32 v2, v2, v70
	v_fma_f32 v3, v3, v70, v102
	v_cvt_pk_bf16_f32 v9, v3, s0
	ds_write_b16 v0, v9
	v_cvt_pk_bf16_f32 v10, v2, s0
	ds_write_b16 v8, v10
	v_mul_f32_e32 v2, v2, v71
	v_fma_f32 v3, v3, v71, v103
	v_cvt_pk_bf16_f32 v11, v3, s0
	ds_write_b16 v0, v11 offset:272
	v_cvt_pk_bf16_f32 v12, v2, s0
	ds_write_b16 v8, v12 offset:272
	v_mul_f32_e32 v2, v2, v72
	v_fma_f32 v3, v3, v72, v104
	v_cvt_pk_bf16_f32 v9, v3, s0
	ds_write_b16 v0, v9 offset:544
	v_cvt_pk_bf16_f32 v10, v2, s0
	ds_write_b16 v8, v10 offset:544
	v_mul_f32_e32 v2, v2, v73
	v_fma_f32 v3, v3, v73, v105
	v_cvt_pk_bf16_f32 v11, v3, s0
	ds_write_b16 v0, v11 offset:816
	v_cvt_pk_bf16_f32 v12, v2, s0
	ds_write_b16 v8, v12 offset:816
	v_mul_f32_e32 v2, v2, v74
	v_fma_f32 v3, v3, v74, v106
	v_cvt_pk_bf16_f32 v9, v3, s0
	ds_write_b16 v0, v9 offset:1088
	v_cvt_pk_bf16_f32 v10, v2, s0
	ds_write_b16 v8, v10 offset:1088
	v_mul_f32_e32 v2, v2, v75
	v_fma_f32 v3, v3, v75, v107
	v_cvt_pk_bf16_f32 v11, v3, s0
	ds_write_b16 v0, v11 offset:1360
	v_cvt_pk_bf16_f32 v12, v2, s0
	ds_write_b16 v8, v12 offset:1360
	v_mul_f32_e32 v2, v2, v76
	v_fma_f32 v3, v3, v76, v108
	v_cvt_pk_bf16_f32 v9, v3, s0
	ds_write_b16 v0, v9 offset:1632
	v_cvt_pk_bf16_f32 v10, v2, s0
	ds_write_b16 v8, v10 offset:1632
	v_mul_f32_e32 v2, v2, v77
	v_fma_f32 v3, v3, v77, v109
	v_cvt_pk_bf16_f32 v11, v3, s0
	ds_write_b16 v0, v11 offset:1904
	v_cvt_pk_bf16_f32 v12, v2, s0
	ds_write_b16 v8, v12 offset:1904
	v_mul_f32_e32 v2, v2, v78
	v_fma_f32 v3, v3, v78, v110
	v_cvt_pk_bf16_f32 v9, v3, s0
	ds_write_b16 v0, v9 offset:2176
	v_cvt_pk_bf16_f32 v10, v2, s0
	ds_write_b16 v8, v10 offset:2176
	v_mul_f32_e32 v2, v2, v79
	v_fma_f32 v3, v3, v79, v111
	v_cvt_pk_bf16_f32 v11, v3, s0
	ds_write_b16 v0, v11 offset:2448
	v_cvt_pk_bf16_f32 v12, v2, s0
	ds_write_b16 v8, v12 offset:2448
	v_mul_f32_e32 v2, v2, v80
	v_fma_f32 v3, v3, v80, v112
	v_cvt_pk_bf16_f32 v9, v3, s0
	ds_write_b16 v0, v9 offset:2720
	v_cvt_pk_bf16_f32 v10, v2, s0
	ds_write_b16 v8, v10 offset:2720
	v_mul_f32_e32 v2, v2, v81
	v_fma_f32 v3, v3, v81, v113
	v_cvt_pk_bf16_f32 v11, v3, s0
	ds_write_b16 v0, v11 offset:2992
	v_cvt_pk_bf16_f32 v12, v2, s0
	ds_write_b16 v8, v12 offset:2992
	v_mul_f32_e32 v2, v2, v82
	v_fma_f32 v3, v3, v82, v114
	v_cvt_pk_bf16_f32 v9, v3, s0
	ds_write_b16 v0, v9 offset:3264
	v_cvt_pk_bf16_f32 v10, v2, s0
	ds_write_b16 v8, v10 offset:3264
	v_mul_f32_e32 v2, v2, v83
	v_fma_f32 v3, v3, v83, v115
	v_cvt_pk_bf16_f32 v11, v3, s0
	ds_write_b16 v0, v11 offset:3536
	v_cvt_pk_bf16_f32 v12, v2, s0
	ds_write_b16 v8, v12 offset:3536
	v_mul_f32_e32 v2, v2, v84
	v_fma_f32 v3, v3, v84, v116
	v_cvt_pk_bf16_f32 v9, v3, s0
	ds_write_b16 v0, v9 offset:3808
	v_cvt_pk_bf16_f32 v10, v2, s0
	ds_write_b16 v8, v10 offset:3808
	v_mul_f32_e32 v2, v2, v85
	v_fma_f32 v3, v3, v85, v117
	v_cvt_pk_bf16_f32 v11, v3, s0
	ds_write_b16 v0, v11 offset:4080
	v_cvt_pk_bf16_f32 v12, v2, s0
	ds_write_b16 v8, v12 offset:4080
	v_mul_f32_e32 v2, v2, v86
	v_fma_f32 v3, v3, v86, v118
	v_cvt_pk_bf16_f32 v9, v3, s0
	ds_write_b16 v0, v9 offset:4352
	v_cvt_pk_bf16_f32 v10, v2, s0
	ds_write_b16 v8, v10 offset:4352
	v_mul_f32_e32 v2, v2, v87
	v_fma_f32 v3, v3, v87, v119
	v_cvt_pk_bf16_f32 v11, v3, s0
	ds_write_b16 v0, v11 offset:4624
	v_cvt_pk_bf16_f32 v12, v2, s0
	ds_write_b16 v8, v12 offset:4624
	v_mul_f32_e32 v2, v2, v88
	v_fma_f32 v3, v3, v88, v120
	v_cvt_pk_bf16_f32 v9, v3, s0
	ds_write_b16 v0, v9 offset:4896
	v_cvt_pk_bf16_f32 v10, v2, s0
	ds_write_b16 v8, v10 offset:4896
	v_mul_f32_e32 v2, v2, v89
	v_fma_f32 v3, v3, v89, v121
	v_cvt_pk_bf16_f32 v11, v3, s0
	ds_write_b16 v0, v11 offset:5168
	v_cvt_pk_bf16_f32 v12, v2, s0
	ds_write_b16 v8, v12 offset:5168
	v_mul_f32_e32 v2, v2, v90
	v_fma_f32 v3, v3, v90, v122
	v_cvt_pk_bf16_f32 v9, v3, s0
	ds_write_b16 v0, v9 offset:5440
	v_cvt_pk_bf16_f32 v10, v2, s0
	ds_write_b16 v8, v10 offset:5440
	v_mul_f32_e32 v2, v2, v91
	v_fma_f32 v3, v3, v91, v123
	v_cvt_pk_bf16_f32 v11, v3, s0
	ds_write_b16 v0, v11 offset:5712
	v_cvt_pk_bf16_f32 v12, v2, s0
	ds_write_b16 v8, v12 offset:5712
	v_mul_f32_e32 v2, v2, v92
	v_fma_f32 v3, v3, v92, v124
	v_cvt_pk_bf16_f32 v9, v3, s0
	ds_write_b16 v0, v9 offset:5984
	v_cvt_pk_bf16_f32 v10, v2, s0
	ds_write_b16 v8, v10 offset:5984
	v_mul_f32_e32 v2, v2, v93
	v_fma_f32 v3, v3, v93, v125
	v_cvt_pk_bf16_f32 v11, v3, s0
	ds_write_b16 v0, v11 offset:6256
	v_cvt_pk_bf16_f32 v12, v2, s0
	ds_write_b16 v8, v12 offset:6256
	v_mul_f32_e32 v2, v2, v94
	v_fma_f32 v3, v3, v94, v126
	v_cvt_pk_bf16_f32 v9, v3, s0
	ds_write_b16 v0, v9 offset:6528
	v_cvt_pk_bf16_f32 v10, v2, s0
	ds_write_b16 v8, v10 offset:6528
	v_mul_f32_e32 v2, v2, v95
	v_fma_f32 v3, v3, v95, v127
	v_cvt_pk_bf16_f32 v11, v3, s0
	ds_write_b16 v0, v11 offset:6800
	v_cvt_pk_bf16_f32 v12, v2, s0
	ds_write_b16 v8, v12 offset:6800
	v_mul_f32_e32 v2, v2, v96
	v_fma_f32 v3, v3, v96, v128
	v_cvt_pk_bf16_f32 v9, v3, s0
	ds_write_b16 v0, v9 offset:7072
	v_cvt_pk_bf16_f32 v10, v2, s0
	ds_write_b16 v8, v10 offset:7072
	v_mul_f32_e32 v2, v2, v97
	v_fma_f32 v3, v3, v97, v129
	v_cvt_pk_bf16_f32 v11, v3, s0
	ds_write_b16 v0, v11 offset:7344
	v_cvt_pk_bf16_f32 v12, v2, s0
	ds_write_b16 v8, v12 offset:7344
	v_mul_f32_e32 v2, v2, v98
	v_fma_f32 v3, v3, v98, v130
	v_cvt_pk_bf16_f32 v9, v3, s0
	ds_write_b16 v0, v9 offset:7616
	v_cvt_pk_bf16_f32 v10, v2, s0
	ds_write_b16 v8, v10 offset:7616
	v_mul_f32_e32 v2, v2, v99
	v_fma_f32 v3, v3, v99, v131
	v_cvt_pk_bf16_f32 v11, v3, s0
	ds_write_b16 v0, v11 offset:7888
	v_cvt_pk_bf16_f32 v12, v2, s0
	ds_write_b16 v8, v12 offset:7888
	v_mul_f32_e32 v2, v2, v100
	v_fma_f32 v3, v3, v100, v132
	v_cvt_pk_bf16_f32 v9, v3, s0
	ds_write_b16 v0, v9 offset:8160
	v_cvt_pk_bf16_f32 v10, v2, s0
	ds_write_b16 v8, v10 offset:8160
	v_mul_f32_e32 v2, v2, v101
	v_fma_f32 v3, v3, v101, v133
	v_cvt_pk_bf16_f32 v11, v3, s0
	ds_write_b16 v0, v11 offset:8432
	v_cvt_pk_bf16_f32 v12, v2, s0
	ds_write_b16 v8, v12 offset:8432
	v_add_u32_e32 v5, 0x4080, v4
	ds_read2_b32 v[70:71], v5 offset1:129
	v_add_u32_e32 v6, 0xc180, v4
	ds_read2_b32 v[102:103], v6 offset1:129
	v_add_u32_e32 v5, 0x4488, v4
	ds_read2_b32 v[72:73], v5 offset1:129
	v_add_u32_e32 v6, 0xc588, v4
	ds_read2_b32 v[104:105], v6 offset1:129
	v_add_u32_e32 v5, 0x4890, v4
	ds_read2_b32 v[74:75], v5 offset1:129
	v_add_u32_e32 v6, 0xc990, v4
	ds_read2_b32 v[106:107], v6 offset1:129
	v_add_u32_e32 v5, 0x4c98, v4
	ds_read2_b32 v[76:77], v5 offset1:129
	v_add_u32_e32 v6, 0xcd98, v4
	ds_read2_b32 v[108:109], v6 offset1:129
	v_add_u32_e32 v5, 0x50a0, v4
	ds_read2_b32 v[78:79], v5 offset1:129
	v_add_u32_e32 v6, 0xd1a0, v4
	ds_read2_b32 v[110:111], v6 offset1:129
	v_add_u32_e32 v5, 0x54a8, v4
	ds_read2_b32 v[80:81], v5 offset1:129
	v_add_u32_e32 v6, 0xd5a8, v4
	ds_read2_b32 v[112:113], v6 offset1:129
	v_add_u32_e32 v5, 0x58b0, v4
	ds_read2_b32 v[82:83], v5 offset1:129
	v_add_u32_e32 v6, 0xd9b0, v4
	ds_read2_b32 v[114:115], v6 offset1:129
	v_add_u32_e32 v5, 0x5cb8, v4
	ds_read2_b32 v[84:85], v5 offset1:129
	v_add_u32_e32 v6, 0xddb8, v4
	ds_read2_b32 v[116:117], v6 offset1:129
	v_add_u32_e32 v5, 0x60c0, v4
	ds_read2_b32 v[86:87], v5 offset1:129
	v_add_u32_e32 v6, 0xe1c0, v4
	ds_read2_b32 v[118:119], v6 offset1:129
	v_add_u32_e32 v5, 0x64c8, v4
	ds_read2_b32 v[88:89], v5 offset1:129
	v_add_u32_e32 v6, 0xe5c8, v4
	ds_read2_b32 v[120:121], v6 offset1:129
	v_add_u32_e32 v5, 0x68d0, v4
	ds_read2_b32 v[90:91], v5 offset1:129
	v_add_u32_e32 v6, 0xe9d0, v4
	ds_read2_b32 v[122:123], v6 offset1:129
	v_add_u32_e32 v5, 0x6cd8, v4
	ds_read2_b32 v[92:93], v5 offset1:129
	v_add_u32_e32 v6, 0xedd8, v4
	ds_read2_b32 v[124:125], v6 offset1:129
	v_add_u32_e32 v5, 0x70e0, v4
	ds_read2_b32 v[94:95], v5 offset1:129
	v_add_u32_e32 v6, 0xf1e0, v4
	ds_read2_b32 v[126:127], v6 offset1:129
	v_add_u32_e32 v5, 0x74e8, v4
	ds_read2_b32 v[96:97], v5 offset1:129
	v_add_u32_e32 v6, 0xf5e8, v4
	ds_read2_b32 v[128:129], v6 offset1:129
	v_add_u32_e32 v5, 0x78f0, v4
	ds_read2_b32 v[98:99], v5 offset1:129
	v_add_u32_e32 v6, 0xf9f0, v4
	ds_read2_b32 v[130:131], v6 offset1:129
	v_add_u32_e32 v5, 0x7cf8, v4
	ds_read2_b32 v[100:101], v5 offset1:129
	v_add_u32_e32 v6, 0xfdf8, v4
	ds_read2_b32 v[132:133], v6 offset1:129
	s_waitcnt lgkmcnt(0)
	v_mul_f32_e32 v2, v2, v70
	v_fma_f32 v3, v3, v70, v102
	v_cvt_pk_bf16_f32 v9, v3, s0
	ds_write_b16 v0, v9 offset:8704
	v_cvt_pk_bf16_f32 v10, v2, s0
	ds_write_b16 v8, v10 offset:8704
	v_mul_f32_e32 v2, v2, v71
	v_fma_f32 v3, v3, v71, v103
	v_cvt_pk_bf16_f32 v11, v3, s0
	ds_write_b16 v0, v11 offset:8976
	v_cvt_pk_bf16_f32 v12, v2, s0
	ds_write_b16 v8, v12 offset:8976
	v_mul_f32_e32 v2, v2, v72
	v_fma_f32 v3, v3, v72, v104
	v_cvt_pk_bf16_f32 v9, v3, s0
	ds_write_b16 v0, v9 offset:9248
	v_cvt_pk_bf16_f32 v10, v2, s0
	ds_write_b16 v8, v10 offset:9248
	v_mul_f32_e32 v2, v2, v73
	v_fma_f32 v3, v3, v73, v105
	v_cvt_pk_bf16_f32 v11, v3, s0
	ds_write_b16 v0, v11 offset:9520
	v_cvt_pk_bf16_f32 v12, v2, s0
	ds_write_b16 v8, v12 offset:9520
	v_mul_f32_e32 v2, v2, v74
	v_fma_f32 v3, v3, v74, v106
	v_cvt_pk_bf16_f32 v9, v3, s0
	ds_write_b16 v0, v9 offset:9792
	v_cvt_pk_bf16_f32 v10, v2, s0
	ds_write_b16 v8, v10 offset:9792
	v_mul_f32_e32 v2, v2, v75
	v_fma_f32 v3, v3, v75, v107
	v_cvt_pk_bf16_f32 v11, v3, s0
	ds_write_b16 v0, v11 offset:10064
	v_cvt_pk_bf16_f32 v12, v2, s0
	ds_write_b16 v8, v12 offset:10064
	v_mul_f32_e32 v2, v2, v76
	v_fma_f32 v3, v3, v76, v108
	v_cvt_pk_bf16_f32 v9, v3, s0
	ds_write_b16 v0, v9 offset:10336
	v_cvt_pk_bf16_f32 v10, v2, s0
	ds_write_b16 v8, v10 offset:10336
	v_mul_f32_e32 v2, v2, v77
	v_fma_f32 v3, v3, v77, v109
	v_cvt_pk_bf16_f32 v11, v3, s0
	ds_write_b16 v0, v11 offset:10608
	v_cvt_pk_bf16_f32 v12, v2, s0
	ds_write_b16 v8, v12 offset:10608
	v_mul_f32_e32 v2, v2, v78
	v_fma_f32 v3, v3, v78, v110
	v_cvt_pk_bf16_f32 v9, v3, s0
	ds_write_b16 v0, v9 offset:10880
	v_cvt_pk_bf16_f32 v10, v2, s0
	ds_write_b16 v8, v10 offset:10880
	v_mul_f32_e32 v2, v2, v79
	v_fma_f32 v3, v3, v79, v111
	v_cvt_pk_bf16_f32 v11, v3, s0
	ds_write_b16 v0, v11 offset:11152
	v_cvt_pk_bf16_f32 v12, v2, s0
	ds_write_b16 v8, v12 offset:11152
	v_mul_f32_e32 v2, v2, v80
	v_fma_f32 v3, v3, v80, v112
	v_cvt_pk_bf16_f32 v9, v3, s0
	ds_write_b16 v0, v9 offset:11424
	v_cvt_pk_bf16_f32 v10, v2, s0
	ds_write_b16 v8, v10 offset:11424
	v_mul_f32_e32 v2, v2, v81
	v_fma_f32 v3, v3, v81, v113
	v_cvt_pk_bf16_f32 v11, v3, s0
	ds_write_b16 v0, v11 offset:11696
	v_cvt_pk_bf16_f32 v12, v2, s0
	ds_write_b16 v8, v12 offset:11696
	v_mul_f32_e32 v2, v2, v82
	v_fma_f32 v3, v3, v82, v114
	v_cvt_pk_bf16_f32 v9, v3, s0
	ds_write_b16 v0, v9 offset:11968
	v_cvt_pk_bf16_f32 v10, v2, s0
	ds_write_b16 v8, v10 offset:11968
	v_mul_f32_e32 v2, v2, v83
	v_fma_f32 v3, v3, v83, v115
	v_cvt_pk_bf16_f32 v11, v3, s0
	ds_write_b16 v0, v11 offset:12240
	v_cvt_pk_bf16_f32 v12, v2, s0
	ds_write_b16 v8, v12 offset:12240
	v_mul_f32_e32 v2, v2, v84
	v_fma_f32 v3, v3, v84, v116
	v_cvt_pk_bf16_f32 v9, v3, s0
	ds_write_b16 v0, v9 offset:12512
	v_cvt_pk_bf16_f32 v10, v2, s0
	ds_write_b16 v8, v10 offset:12512
	v_mul_f32_e32 v2, v2, v85
	v_fma_f32 v3, v3, v85, v117
	v_cvt_pk_bf16_f32 v11, v3, s0
	ds_write_b16 v0, v11 offset:12784
	v_cvt_pk_bf16_f32 v12, v2, s0
	ds_write_b16 v8, v12 offset:12784
	v_mul_f32_e32 v2, v2, v86
	v_fma_f32 v3, v3, v86, v118
	v_cvt_pk_bf16_f32 v9, v3, s0
	ds_write_b16 v0, v9 offset:13056
	v_cvt_pk_bf16_f32 v10, v2, s0
	ds_write_b16 v8, v10 offset:13056
	v_mul_f32_e32 v2, v2, v87
	v_fma_f32 v3, v3, v87, v119
	v_cvt_pk_bf16_f32 v11, v3, s0
	ds_write_b16 v0, v11 offset:13328
	v_cvt_pk_bf16_f32 v12, v2, s0
	ds_write_b16 v8, v12 offset:13328
	v_mul_f32_e32 v2, v2, v88
	v_fma_f32 v3, v3, v88, v120
	v_cvt_pk_bf16_f32 v9, v3, s0
	ds_write_b16 v0, v9 offset:13600
	v_cvt_pk_bf16_f32 v10, v2, s0
	ds_write_b16 v8, v10 offset:13600
	v_mul_f32_e32 v2, v2, v89
	v_fma_f32 v3, v3, v89, v121
	v_cvt_pk_bf16_f32 v11, v3, s0
	ds_write_b16 v0, v11 offset:13872
	v_cvt_pk_bf16_f32 v12, v2, s0
	ds_write_b16 v8, v12 offset:13872
	v_mul_f32_e32 v2, v2, v90
	v_fma_f32 v3, v3, v90, v122
	v_cvt_pk_bf16_f32 v9, v3, s0
	ds_write_b16 v0, v9 offset:14144
	v_cvt_pk_bf16_f32 v10, v2, s0
	ds_write_b16 v8, v10 offset:14144
	v_mul_f32_e32 v2, v2, v91
	v_fma_f32 v3, v3, v91, v123
	v_cvt_pk_bf16_f32 v11, v3, s0
	ds_write_b16 v0, v11 offset:14416
	v_cvt_pk_bf16_f32 v12, v2, s0
	ds_write_b16 v8, v12 offset:14416
	v_mul_f32_e32 v2, v2, v92
	v_fma_f32 v3, v3, v92, v124
	v_cvt_pk_bf16_f32 v9, v3, s0
	ds_write_b16 v0, v9 offset:14688
	v_cvt_pk_bf16_f32 v10, v2, s0
	ds_write_b16 v8, v10 offset:14688
	v_mul_f32_e32 v2, v2, v93
	v_fma_f32 v3, v3, v93, v125
	v_cvt_pk_bf16_f32 v11, v3, s0
	ds_write_b16 v0, v11 offset:14960
	v_cvt_pk_bf16_f32 v12, v2, s0
	ds_write_b16 v8, v12 offset:14960
	v_mul_f32_e32 v2, v2, v94
	v_fma_f32 v3, v3, v94, v126
	v_cvt_pk_bf16_f32 v9, v3, s0
	ds_write_b16 v0, v9 offset:15232
	v_cvt_pk_bf16_f32 v10, v2, s0
	ds_write_b16 v8, v10 offset:15232
	v_mul_f32_e32 v2, v2, v95
	v_fma_f32 v3, v3, v95, v127
	v_cvt_pk_bf16_f32 v11, v3, s0
	ds_write_b16 v0, v11 offset:15504
	v_cvt_pk_bf16_f32 v12, v2, s0
	ds_write_b16 v8, v12 offset:15504
	v_mul_f32_e32 v2, v2, v96
	v_fma_f32 v3, v3, v96, v128
	v_cvt_pk_bf16_f32 v9, v3, s0
	ds_write_b16 v0, v9 offset:15776
	v_cvt_pk_bf16_f32 v10, v2, s0
	ds_write_b16 v8, v10 offset:15776
	v_mul_f32_e32 v2, v2, v97
	v_fma_f32 v3, v3, v97, v129
	v_cvt_pk_bf16_f32 v11, v3, s0
	ds_write_b16 v0, v11 offset:16048
	v_cvt_pk_bf16_f32 v12, v2, s0
	ds_write_b16 v8, v12 offset:16048
	v_mul_f32_e32 v2, v2, v98
	v_fma_f32 v3, v3, v98, v130
	v_cvt_pk_bf16_f32 v9, v3, s0
	ds_write_b16 v0, v9 offset:16320
	v_cvt_pk_bf16_f32 v10, v2, s0
	ds_write_b16 v8, v10 offset:16320
	v_mul_f32_e32 v2, v2, v99
	v_fma_f32 v3, v3, v99, v131
	v_cvt_pk_bf16_f32 v11, v3, s0
	ds_write_b16 v0, v11 offset:16592
	v_cvt_pk_bf16_f32 v12, v2, s0
	ds_write_b16 v8, v12 offset:16592
	v_mul_f32_e32 v2, v2, v100
	v_fma_f32 v3, v3, v100, v132
	v_cvt_pk_bf16_f32 v9, v3, s0
	ds_write_b16 v0, v9 offset:16864
	v_cvt_pk_bf16_f32 v10, v2, s0
	ds_write_b16 v8, v10 offset:16864
	v_mul_f32_e32 v2, v2, v101
	v_fma_f32 v3, v3, v101, v133
	v_cvt_pk_bf16_f32 v11, v3, s0
	ds_write_b16 v0, v11 offset:17136
	v_cvt_pk_bf16_f32 v12, v2, s0
	ds_write_b16 v8, v12 offset:17136
	s_mul_i32 s4, s26, 0x300
	s_add_i32 s4, s4, s68
	v_add_u32_e32 v4, s4, v39
	v_ashrrev_i32_e32 v5, 31, v4
	v_readlane_b32 s4, v249, 34
	v_lshlrev_b64 v[4:5], 2, v[4:5]
	v_readlane_b32 s5, v249, 35
	s_nop 1
	v_lshl_add_u64 v[6:7], s[4:5], 0, v[4:5]
	v_readlane_b32 s4, v249, 36
	v_readlane_b32 s5, v249, 37
	global_store_dword v[6:7], v2, off
	s_nop 0
	v_lshl_add_u64 v[4:5], s[4:5], 0, v[4:5]
	global_store_dword v[4:5], v3, off
